# DSA far tiles: top-k bit test folded into the fma addend (bfe_i32+bfi, no vcc round trips or s_nop), per-bit v_and extraction moved to the near-diagonal path only
# speedup vs baseline: 1.0162x; 1.0085x over previous
; DI int crow(int reg, int hi) { return (reg & 3) + 8 * (reg >> 2) + 4 * hi; }
; template <int DQK, int W1, int DV, int VW, int MODE> ...
;     ...
;       s[0] = s_block<KSTR, ND, 0>(bufa + klane, qf, negm);
;       s[1] = s_block<KSTR, ND, 1>(bufa + klane, qf, negm);
;       if (MODE == 0) {
;         if (__builtin_amdgcn_readfirstlane((int)(kb + 63 > tq0))) {
; #pragma unroll
;           for (int n = 0; n < 2; ++n)
; #pragma unroll
;             for (int i = 0; i < 16; ++i) { const int key = kb + 32 * n + crow(i, hi); if (key > tq) s[n][i] = NEGV; }
;         }
;       } else if (MODE == 1) {
;         const bool far = (tq0 - (kb + 63)) >= 128;
; #pragma unroll
;         for (int n = 0; n < 2; ++n) {
;           const unsigned wb = (n ? mw1 : mw0) >> (4 * hi);
;           if (far) {
; #pragma unroll
;             for (int i = 0; i < 16; ++i) {
;               const float v = fmaf(s[n][i], c2, bias_far);
;               s[n][i] = ((wb >> ((i & 3) + 8 * (i >> 2))) & 1u) ? v : NEGV;
;             }
;           } else {
; #pragma unroll
;             for (int i = 0; i < 16; ++i) {
;               const int key = kb + 32 * n + crow(i, hi);
;               int rel = tq - key; rel = rel < 0 ? 0 : (rel > 128 ? 128 : rel);
;               const float v = fmaf(s[n][i], c2, lutw[rel]);
;               s[n][i] = ((wb >> ((i & 3) + 8 * (i >> 2))) & 1u) ? v : NEGV;
;             }
;           }
.LBB0_1334:
	s_mov_b32 s54, s100
	v_add_u32_e32 v0, s54, v83
	ds_read_b128 v[34:37], v0
	ds_read_b128 v[38:41], v0 offset:32
	ds_read_b128 v[42:45], v0 offset:64
	ds_read_b128 v[46:49], v0 offset:96
	ds_read_b128 v[212:215], v0 offset:4608
	ds_read_b128 v[102:105], v0 offset:4640
	ds_read_b128 v[106:109], v0 offset:4672
	ds_read_b128 v[110:113], v0 offset:4704
	v_lshrrev_b32_e32 v121, v82, v116
	s_cmpk_lt_i32 s86, 0x80
	s_cselect_b64 s[18:19], -1, 0
	s_cmpk_gt_i32 s86, 0x7f
	s_mov_b64 s[0:1], -1
	s_waitcnt lgkmcnt(7)
	v_mfma_f32_32x32x16_bf16 v[50:65], v[34:37], v[66:69], 0
	v_add_u32_e32 v0, s86, v118
	s_waitcnt lgkmcnt(6)
	v_mfma_f32_32x32x16_bf16 v[50:65], v[38:41], v[70:73], v[50:65]
	s_waitcnt lgkmcnt(5)
	v_mfma_f32_32x32x16_bf16 v[50:65], v[42:45], v[74:77], v[50:65]
	s_waitcnt lgkmcnt(4)
	v_mfma_f32_32x32x16_bf16 v[50:65], v[46:49], v[78:81], v[50:65]
	s_waitcnt lgkmcnt(3)
	v_mfma_f32_32x32x16_bf16 v[34:49], v[212:215], v[66:69], 0
	s_waitcnt lgkmcnt(2)
	v_mfma_f32_32x32x16_bf16 v[34:49], v[102:105], v[70:73], v[34:49]
	s_waitcnt lgkmcnt(1)
	v_mfma_f32_32x32x16_bf16 v[34:49], v[106:109], v[74:77], v[34:49]
	s_waitcnt lgkmcnt(0)
	v_mfma_f32_32x32x16_bf16 v[34:49], v[110:113], v[78:81], v[34:49]
	s_cbranch_scc1 .LBB0_1336
	v_and_b32_e32 v122, 0x4000000, v121
	v_and_b32_e32 v135, 2, v121
	v_and_b32_e32 v136, 1, v121
	v_and_b32_e32 v133, 8, v121
	v_and_b32_e32 v134, 4, v121
	v_and_b32_e32 v130, 0x200, v121
	v_and_b32_e32 v132, 0x100, v121
	v_and_b32_e32 v128, 0x800, v121
	v_and_b32_e32 v131, 0x400, v121
	v_and_b32_e32 v127, 0x20000, v121
	v_and_b32_e32 v129, 0x10000, v121
	v_and_b32_e32 v125, 0x80000, v121
	v_and_b32_e32 v126, 0x40000, v121
	v_and_b32_e32 v123, 0x2000000, v121
	v_and_b32_e32 v124, 0x1000000, v121
	v_cmp_ne_u32_e32 vcc, 0, v122
	v_add_u32_e32 v102, 0xfffff85f, v0
	v_add_u32_e32 v103, 0xfffff85e, v0
	v_med3_i32 v102, v102, 0, v233
	v_med3_i32 v103, v103, 0, v233
	v_lshl_add_u32 v102, v102, 2, s27
	v_lshl_add_u32 v103, v103, 2, s27
	v_add_u32_e32 v104, 0xfffff85d, v0
	v_add_u32_e32 v105, 0xfffff85c, v0
	ds_read_b32 v102, v102
	ds_read_b32 v103, v103
	v_med3_i32 v104, v104, 0, v233
	v_med3_i32 v105, v105, 0, v233
	v_lshl_add_u32 v104, v104, 2, s27
	v_lshl_add_u32 v105, v105, 2, s27
	v_add_u32_e32 v106, 0xfffff857, v0
	v_add_u32_e32 v107, 0xfffff856, v0
	ds_read_b32 v104, v104
	ds_read_b32 v105, v105
	v_med3_i32 v106, v106, 0, v233
	v_med3_i32 v107, v107, 0, v233
	v_add_u32_e32 v108, 0xfffff855, v0
	v_add_u32_e32 v109, 0xfffff854, v0
	v_lshl_add_u32 v106, v106, 2, s27
	v_lshl_add_u32 v107, v107, 2, s27
	v_med3_i32 v108, v108, 0, v233
	v_med3_i32 v109, v109, 0, v233
	ds_read_b32 v106, v106
	ds_read_b32 v107, v107
	v_lshl_add_u32 v108, v108, 2, s27
	v_lshl_add_u32 v109, v109, 2, s27
	v_cmp_ne_u32_e64 s[0:1], 0, v136
	ds_read_b32 v108, v108
	ds_read_b32 v109, v109
	s_waitcnt lgkmcnt(0)
	v_pk_fma_f32 v[102:103], v[50:51], s[64:65], v[102:103] op_sel_hi:[1,0,1]
	v_add_u32_e32 v110, 0xfffff84f, v0
	v_add_u32_e32 v111, 0xfffff84e, v0
	v_cndmask_b32_e64 v102, v232, v102, s[0:1]
	v_cmp_ne_u32_e64 s[0:1], 0, v135
	v_med3_i32 v110, v110, 0, v233
	v_med3_i32 v111, v111, 0, v233
	v_cndmask_b32_e64 v103, v232, v103, s[0:1]
	v_pk_fma_f32 v[104:105], v[52:53], s[64:65], v[104:105] op_sel_hi:[1,0,1]
	v_cmp_ne_u32_e64 s[0:1], 0, v134
	v_lshl_add_u32 v110, v110, 2, s27
	v_lshl_add_u32 v111, v111, 2, s27
	v_add_u32_e32 v112, 0xfffff84d, v0
	v_add_u32_e32 v113, 0xfffff84c, v0
	v_cndmask_b32_e64 v104, v232, v104, s[0:1]
	v_cmp_ne_u32_e64 s[0:1], 0, v133
	ds_read_b32 v110, v110
	ds_read_b32 v111, v111
	v_med3_i32 v112, v112, 0, v233
	v_med3_i32 v113, v113, 0, v233
	v_cndmask_b32_e64 v105, v232, v105, s[0:1]
	v_pk_fma_f32 v[106:107], v[54:55], s[64:65], v[106:107] op_sel_hi:[1,0,1]
	v_cmp_ne_u32_e64 s[0:1], 0, v132
	v_lshl_add_u32 v112, v112, 2, s27
	v_lshl_add_u32 v113, v113, 2, s27
	v_add_u32_e32 v114, 0xfffff847, v0
	v_add_u32_e32 v115, 0xfffff846, v0
	v_cndmask_b32_e64 v106, v232, v106, s[0:1]
	v_cmp_ne_u32_e64 s[0:1], 0, v130
	ds_read_b32 v112, v112
	ds_read_b32 v113, v113
	v_med3_i32 v114, v114, 0, v233
	v_med3_i32 v115, v115, 0, v233
	v_add_u32_e32 v116, 0xfffff845, v0
	v_add_u32_e32 v120, 0xfffff844, v0
	v_cndmask_b32_e64 v107, v232, v107, s[0:1]
	v_pk_fma_f32 v[108:109], v[56:57], s[64:65], v[108:109] op_sel_hi:[1,0,1]
	v_cmp_ne_u32_e64 s[0:1], 0, v131
	v_lshl_add_u32 v114, v114, 2, s27
	v_lshl_add_u32 v115, v115, 2, s27
	v_med3_i32 v116, v116, 0, v233
	v_med3_i32 v120, v120, 0, v233
	v_cndmask_b32_e64 v108, v232, v108, s[0:1]
	v_cmp_ne_u32_e64 s[0:1], 0, v128
	ds_read_b32 v114, v114
	ds_read_b32 v115, v115
	v_lshl_add_u32 v116, v116, 2, s27
	v_lshl_add_u32 v120, v120, 2, s27
	v_cndmask_b32_e64 v109, v232, v109, s[0:1]
	v_cmp_ne_u32_e64 s[0:1], 0, v129
	ds_read_b32 v116, v116
	ds_read_b32 v120, v120
	s_waitcnt lgkmcnt(0)
	v_pk_fma_f32 v[110:111], v[58:59], s[64:65], v[110:111] op_sel_hi:[1,0,1]
	v_pk_fma_f32 v[112:113], v[60:61], s[64:65], v[112:113] op_sel_hi:[1,0,1]
	v_cndmask_b32_e64 v110, v232, v110, s[0:1]
	v_cmp_ne_u32_e64 s[0:1], 0, v127
	v_pk_fma_f32 v[114:115], v[62:63], s[64:65], v[114:115] op_sel_hi:[1,0,1]
	v_fmac_f32_e32 v116, 0x3e38aa3b, v64
	v_cndmask_b32_e64 v111, v232, v111, s[0:1]
	v_cmp_ne_u32_e64 s[0:1], 0, v126
	v_cndmask_b32_e32 v116, v232, v116, vcc
	v_fmac_f32_e32 v120, 0x3e38aa3b, v65
	v_cndmask_b32_e64 v112, v232, v112, s[0:1]
	v_cmp_ne_u32_e64 s[0:1], 0, v125
	s_nop 1
	v_cndmask_b32_e64 v113, v232, v113, s[0:1]
	v_cmp_ne_u32_e64 s[0:1], 0, v124
	s_nop 1
	v_cndmask_b32_e64 v114, v232, v114, s[0:1]
	v_cmp_ne_u32_e64 s[0:1], 0, v123
	s_nop 1
	v_cndmask_b32_e64 v115, v232, v115, s[0:1]
	s_mov_b64 s[0:1], 0
; template <int DQK, int W1, int DV, int VW, int MODE> ...
;     ...
;           const unsigned wb = (n ? mw1 : mw0) >> (4 * hi);
;           if (far) {
; #pragma unroll
;             for (int i = 0; i < 16; ++i) {
;               const float v = fmaf(s[n][i], c2, bias_far);
;               s[n][i] = ((wb >> ((i & 3) + 8 * (i >> 2))) & 1u) ? v : NEGV;
;             }
.LBB0_1336:
	s_andn2_b64 vcc, exec, s[0:1]
	s_cbranch_vccnz .LBB0_1338
	s_nop 3
	v_bfe_i32 v102, v121, 0, 1
	v_bfe_i32 v103, v121, 1, 1
	v_bfi_b32 v102, v102, v88, v232
	v_bfi_b32 v103, v103, v89, v232
	v_pk_fma_f32 v[102:103], v[50:51], s[64:65], v[102:103] op_sel_hi:[1,0,1]
	v_bfe_i32 v104, v121, 2, 1
	v_bfe_i32 v105, v121, 3, 1
	v_bfi_b32 v104, v104, v88, v232
	v_bfi_b32 v105, v105, v89, v232
	v_pk_fma_f32 v[104:105], v[52:53], s[64:65], v[104:105] op_sel_hi:[1,0,1]
	v_bfe_i32 v106, v121, 8, 1
	v_bfe_i32 v107, v121, 9, 1
	v_bfi_b32 v106, v106, v88, v232
	v_bfi_b32 v107, v107, v89, v232
	v_pk_fma_f32 v[106:107], v[54:55], s[64:65], v[106:107] op_sel_hi:[1,0,1]
	v_bfe_i32 v108, v121, 10, 1
	v_bfe_i32 v109, v121, 11, 1
	v_bfi_b32 v108, v108, v88, v232
	v_bfi_b32 v109, v109, v89, v232
	v_pk_fma_f32 v[108:109], v[56:57], s[64:65], v[108:109] op_sel_hi:[1,0,1]
	v_bfe_i32 v110, v121, 16, 1
	v_bfe_i32 v111, v121, 17, 1
	v_bfi_b32 v110, v110, v88, v232
	v_bfi_b32 v111, v111, v89, v232
	v_pk_fma_f32 v[110:111], v[58:59], s[64:65], v[110:111] op_sel_hi:[1,0,1]
	v_bfe_i32 v112, v121, 18, 1
	v_bfe_i32 v113, v121, 19, 1
	v_bfi_b32 v112, v112, v88, v232
	v_bfi_b32 v113, v113, v89, v232
	v_pk_fma_f32 v[112:113], v[60:61], s[64:65], v[112:113] op_sel_hi:[1,0,1]
	v_bfe_i32 v114, v121, 24, 1
	v_bfe_i32 v115, v121, 25, 1
	v_bfi_b32 v114, v114, v88, v232
	v_bfi_b32 v115, v115, v89, v232
	v_pk_fma_f32 v[114:115], v[62:63], s[64:65], v[114:115] op_sel_hi:[1,0,1]
	v_bfe_i32 v116, v121, 26, 1
	v_bfi_b32 v116, v116, v88, v232
	v_fma_f32 v116, v64, s64, v116
	v_fmamk_f32 v120, v65, 0x3e38aa3b, v88
; DI int crow(int reg, int hi) { return (reg & 3) + 8 * (reg >> 2) + 4 * hi; }
; template <int DQK, int W1, int DV, int VW, int MODE> ...
;     ...
;         const bool far = (tq0 - (kb + 63)) >= 128;
; #pragma unroll
;         for (int n = 0; n < 2; ++n) {
;           const unsigned wb = (n ? mw1 : mw0) >> (4 * hi);
;           if (far) {
; #pragma unroll
;             for (int i = 0; i < 16; ++i) {
;               const float v = fmaf(s[n][i], c2, bias_far);
;               s[n][i] = ((wb >> ((i & 3) + 8 * (i >> 2))) & 1u) ? v : NEGV;
;             }
;           } else {
; #pragma unroll
;             for (int i = 0; i < 16; ++i) {
;               const int key = kb + 32 * n + crow(i, hi);
;               int rel = tq - key; rel = rel < 0 ? 0 : (rel > 128 ? 128 : rel);
;               const float v = fmaf(s[n][i], c2, lutw[rel]);
;               s[n][i] = ((wb >> ((i & 3) + 8 * (i >> 2))) & 1u) ? v : NEGV;
;             }
;           }
.LBB0_1338:
	s_nop 3
	v_lshrrev_b32_e32 v65, v82, v117
	v_and_b32_e32 v50, 0x8000000, v121
	v_cmp_ne_u32_e64 s[8:9], 0, v50
	s_mov_b64 s[70:71], -1
	s_andn2_b64 vcc, exec, s[18:19]
	s_cbranch_vccnz .LBB0_1340
	v_and_b32_e32 v117, 0x4000000, v65
	v_and_b32_e32 v133, 2, v65
	v_and_b32_e32 v134, 1, v65
	v_and_b32_e32 v131, 8, v65
	v_and_b32_e32 v132, 4, v65
	v_and_b32_e32 v129, 0x200, v65
	v_and_b32_e32 v130, 0x100, v65
	v_and_b32_e32 v127, 0x800, v65
	v_and_b32_e32 v128, 0x400, v65
	v_and_b32_e32 v125, 0x20000, v65
	v_and_b32_e32 v126, 0x10000, v65
	v_and_b32_e32 v123, 0x80000, v65
	v_and_b32_e32 v124, 0x40000, v65
	v_and_b32_e32 v121, 0x2000000, v65
	v_and_b32_e32 v122, 0x1000000, v65
	v_cmp_ne_u32_e64 s[0:1], 0, v117
	v_add_u32_e32 v50, 0xfffff83f, v0
	v_add_u32_e32 v51, 0xfffff83e, v0
	v_med3_i32 v50, v50, 0, v233
	v_med3_i32 v51, v51, 0, v233
	v_lshl_add_u32 v50, v50, 2, s27
	v_lshl_add_u32 v51, v51, 2, s27
	v_add_u32_e32 v52, 0xfffff83d, v0
	v_add_u32_e32 v53, 0xfffff83c, v0
	ds_read_b32 v50, v50
	ds_read_b32 v51, v51
	v_med3_i32 v52, v52, 0, v233
	v_med3_i32 v53, v53, 0, v233
	v_lshl_add_u32 v52, v52, 2, s27
	v_lshl_add_u32 v53, v53, 2, s27
	v_add_u32_e32 v54, 0xfffff837, v0
	v_add_u32_e32 v55, 0xfffff836, v0
	ds_read_b32 v52, v52
	ds_read_b32 v53, v53
	v_med3_i32 v54, v54, 0, v233
	v_med3_i32 v55, v55, 0, v233
	v_add_u32_e32 v56, 0xfffff835, v0
	v_add_u32_e32 v57, 0xfffff834, v0
	v_add_u32_e32 v58, 0xfffff82f, v0
	v_add_u32_e32 v59, 0xfffff82e, v0
	v_add_u32_e32 v60, 0xfffff82d, v0
	v_add_u32_e32 v61, 0xfffff82c, v0
	v_add_u32_e32 v62, 0xfffff827, v0
	v_add_u32_e32 v63, 0xfffff826, v0
	v_add_u32_e32 v64, 0xfffff825, v0
	v_add_u32_e32 v0, 0xfffff824, v0
	v_lshl_add_u32 v54, v54, 2, s27
	v_lshl_add_u32 v55, v55, 2, s27
	v_med3_i32 v56, v56, 0, v233
	v_med3_i32 v0, v0, 0, v233
	ds_read_b32 v54, v54
	ds_read_b32 v55, v55
	v_lshl_add_u32 v56, v56, 2, s27
	v_med3_i32 v57, v57, 0, v233
	v_lshl_add_u32 v0, v0, 2, s27
	v_cmp_ne_u32_e32 vcc, 0, v134
	ds_read_b32 v56, v56
	ds_read_b32 v135, v0
	s_waitcnt lgkmcnt(0)
	v_pk_fma_f32 v[50:51], v[34:35], s[64:65], v[50:51] op_sel_hi:[1,0,1]
	v_lshl_add_u32 v57, v57, 2, s27
	v_cndmask_b32_e32 v50, v232, v50, vcc
	v_cmp_ne_u32_e32 vcc, 0, v133
	ds_read_b32 v57, v57
	v_med3_i32 v58, v58, 0, v233
	v_med3_i32 v59, v59, 0, v233
	v_cndmask_b32_e32 v51, v232, v51, vcc
	v_pk_fma_f32 v[52:53], v[36:37], s[64:65], v[52:53] op_sel_hi:[1,0,1]
	v_cmp_ne_u32_e32 vcc, 0, v132
	v_lshl_add_u32 v58, v58, 2, s27
	v_lshl_add_u32 v59, v59, 2, s27
	v_cndmask_b32_e32 v52, v232, v52, vcc
	v_cmp_ne_u32_e32 vcc, 0, v131
	ds_read_b32 v58, v58
	ds_read_b32 v59, v59
	v_med3_i32 v60, v60, 0, v233
	v_med3_i32 v61, v61, 0, v233
	v_cndmask_b32_e32 v53, v232, v53, vcc
	v_pk_fma_f32 v[54:55], v[38:39], s[64:65], v[54:55] op_sel_hi:[1,0,1]
	v_cmp_ne_u32_e32 vcc, 0, v130
	v_lshl_add_u32 v60, v60, 2, s27
	v_lshl_add_u32 v61, v61, 2, s27
	v_med3_i32 v62, v62, 0, v233
	v_med3_i32 v63, v63, 0, v233
	v_med3_i32 v64, v64, 0, v233
	v_cndmask_b32_e32 v54, v232, v54, vcc
	v_cmp_ne_u32_e32 vcc, 0, v129
	ds_read_b32 v60, v60
	ds_read_b32 v61, v61
	v_lshl_add_u32 v62, v62, 2, s27
	v_lshl_add_u32 v63, v63, 2, s27
	v_lshl_add_u32 v64, v64, 2, s27
	v_cndmask_b32_e32 v55, v232, v55, vcc
	v_cmp_ne_u32_e32 vcc, 0, v128
	ds_read_b32 v62, v62
	ds_read_b32 v63, v63
	ds_read_b32 v64, v64
	s_waitcnt lgkmcnt(0)
	v_pk_fma_f32 v[56:57], v[40:41], s[64:65], v[56:57] op_sel_hi:[1,0,1]
	v_pk_fma_f32 v[58:59], v[42:43], s[64:65], v[58:59] op_sel_hi:[1,0,1]
	v_cndmask_b32_e32 v56, v232, v56, vcc
	v_cmp_ne_u32_e32 vcc, 0, v127
	v_pk_fma_f32 v[60:61], v[44:45], s[64:65], v[60:61] op_sel_hi:[1,0,1]
	v_pk_fma_f32 v[62:63], v[46:47], s[64:65], v[62:63] op_sel_hi:[1,0,1]
	v_cndmask_b32_e32 v57, v232, v57, vcc
	v_cmp_ne_u32_e32 vcc, 0, v126
	v_fmac_f32_e32 v64, 0x3e38aa3b, v48
	v_cndmask_b32_e64 v64, v232, v64, s[0:1]
	v_cndmask_b32_e32 v58, v232, v58, vcc
	v_cmp_ne_u32_e32 vcc, 0, v125
	v_fmac_f32_e32 v135, 0x3e38aa3b, v49
	s_mov_b64 s[70:71], 0
	v_cndmask_b32_e32 v59, v232, v59, vcc
	v_cmp_ne_u32_e32 vcc, 0, v124
	s_nop 1
	v_cndmask_b32_e32 v60, v232, v60, vcc
	v_cmp_ne_u32_e32 vcc, 0, v123
	s_nop 1
	v_cndmask_b32_e32 v61, v232, v61, vcc
	v_cmp_ne_u32_e32 vcc, 0, v122
	s_nop 1
	v_cndmask_b32_e32 v62, v232, v62, vcc
	v_cmp_ne_u32_e32 vcc, 0, v121
	s_nop 1
	v_cndmask_b32_e32 v63, v232, v63, vcc
.LBB0_1340:
	s_andn2_b64 vcc, exec, s[70:71]
	s_cbranch_vccnz .LBB0_1342
	v_bfe_i32 v50, v65, 0, 1
	v_bfe_i32 v51, v65, 1, 1
	v_bfi_b32 v50, v50, v88, v232
	v_bfi_b32 v51, v51, v89, v232
	v_pk_fma_f32 v[50:51], v[34:35], s[64:65], v[50:51] op_sel_hi:[1,0,1]
	v_bfe_i32 v52, v65, 2, 1
	v_bfe_i32 v53, v65, 3, 1
	v_bfi_b32 v52, v52, v88, v232
	v_bfi_b32 v53, v53, v89, v232
	v_pk_fma_f32 v[52:53], v[36:37], s[64:65], v[52:53] op_sel_hi:[1,0,1]
	v_bfe_i32 v54, v65, 8, 1
	v_bfe_i32 v55, v65, 9, 1
	v_bfi_b32 v54, v54, v88, v232
	v_bfi_b32 v55, v55, v89, v232
	v_pk_fma_f32 v[54:55], v[38:39], s[64:65], v[54:55] op_sel_hi:[1,0,1]
	v_bfe_i32 v56, v65, 10, 1
	v_bfe_i32 v57, v65, 11, 1
	v_bfi_b32 v56, v56, v88, v232
	v_bfi_b32 v57, v57, v89, v232
	v_pk_fma_f32 v[56:57], v[40:41], s[64:65], v[56:57] op_sel_hi:[1,0,1]
	v_bfe_i32 v58, v65, 16, 1
	v_bfe_i32 v59, v65, 17, 1
	v_bfi_b32 v58, v58, v88, v232
	v_bfi_b32 v59, v59, v89, v232
	v_pk_fma_f32 v[58:59], v[42:43], s[64:65], v[58:59] op_sel_hi:[1,0,1]
	v_bfe_i32 v60, v65, 18, 1
	v_bfe_i32 v61, v65, 19, 1
	v_bfi_b32 v60, v60, v88, v232
	v_bfi_b32 v61, v61, v89, v232
	v_pk_fma_f32 v[60:61], v[44:45], s[64:65], v[60:61] op_sel_hi:[1,0,1]
	v_bfe_i32 v62, v65, 24, 1
	v_bfe_i32 v63, v65, 25, 1
	v_bfi_b32 v62, v62, v88, v232
	v_bfi_b32 v63, v63, v89, v232
	v_pk_fma_f32 v[62:63], v[46:47], s[64:65], v[62:63] op_sel_hi:[1,0,1]
	v_bfe_i32 v64, v65, 26, 1
	v_bfi_b32 v64, v64, v88, v232
	v_fma_f32 v64, v48, s64, v64
	v_fmamk_f32 v135, v49, 0x3e38aa3b, v88
